# selection rounds: overflow decision taken from the append atomics through a per-round-parity LDS flag, so rounds without a prune use one workgroup barrier instead of two and skip the count re-read
# speedup vs baseline: 1.0001x; 1.0001x over previous
.LBB0_99:
	s_bitcmp0_b32 s8, 0
	v_readlane_b32 s3, v254, 21
	s_cselect_b32 s4, s54, s3
	s_add_i32 s4, s4, s2
	s_cmpk_gt_i32 s4, 0x1ff
	s_cbranch_scc1 .LBB0_98
	v_readlane_b32 s2, v253, 22
	v_mbcnt_lo_u32_b32 v42, -1, 0
	v_mbcnt_hi_u32_b32 v42, -1, v42
	v_writelane_b32 v255, s8, 52
	s_nop 0
	v_or_b32_e32 v0, s2, v42
	v_cmp_gt_i32_e32 vcc, 32, v0
	s_barrier
	s_and_saveexec_b64 s[2:3], vcc
	s_cbranch_execz .LBB0_102
	v_lshl_add_u32 v1, v0, 2, 0
	v_add_u32_e32 v2, 0x24000, v1
	v_add_u32_e32 v1, 0x24080, v1
	ds_write_b32 v2, v41
	v_mov_b32_e32 v2, 0xff800000
	ds_write_b32 v1, v2
	v_mov_b32_e32 v2, 0x25478
	ds_write_b32 v2, v41
	ds_write_b32 v2, v41 offset:4

.LBB0_106:
	v_lshl_add_u32 v40, s78, 2, v43
	v_bfe_u32 v131, v40, 2, 1
	v_lshlrev_b32_e32 v131, 2, v131
	v_add_u32_e32 v131, 0x25478, v131
	v_add_u32_e32 v76, 4, v40
	v_lshlrev_b32_e32 v77, 5, v76
	v_cmp_ge_i32_e32 vcc, s75, v76
	s_nop 1
	v_cndmask_b32_e32 v76, 0, v77, vcc
	v_or_b32_e32 v76, v76, v147
	v_mad_i64_i32 v[88:89], s[2:3], v76, s64, v[106:107]
	global_load_dwordx4 v[76:79], v[88:89], off offset:512
	global_load_dwordx4 v[186:189], v[88:89], off offset:544
	global_load_dwordx4 v[84:87], v[88:89], off offset:576
	s_nop 0
	global_load_dwordx4 v[88:91], v[88:89], off offset:608
	v_cmp_ge_i32_e32 vcc, s75, v40
	s_and_saveexec_b64 s[2:3], vcc
	s_cbranch_execz .LBB0_138
	s_waitcnt vmcnt(4)
	v_mfma_f32_32x32x16_f16 v[8:23], v[116:119], a[64:67], 0
	v_mfma_f32_32x32x16_f16 v[8:23], v[112:115], a[68:71], v[8:23]
	v_mfma_f32_32x32x16_f16 v[8:23], v[108:111], a[72:75], v[8:23]
	v_mfma_f32_32x32x16_f16 v[8:23], v[92:95], a[76:79], v[8:23]
	v_mfma_f32_32x32x16_f16 v[24:39], v[116:119], a[80:83], 0
	v_mfma_f32_32x32x16_f16 v[24:39], v[112:115], a[84:87], v[24:39]
	v_mfma_f32_32x32x16_f16 v[24:39], v[108:111], a[88:91], v[24:39]
	v_mfma_f32_32x32x16_f16 v[24:39], v[92:95], a[92:95], v[24:39]
	v_mfma_f32_32x32x16_f16 v[44:59], v[116:119], a[96:99], 0
	v_max_i32_e32 v8, 0, v8
	v_max_i32_e32 v9, 0, v9
	v_mul_f32_e32 v60, v72, v8
	v_mul_f32_e32 v61, v72, v9
	v_max_i32_e32 v10, 0, v10
	v_max_i32_e32 v11, 0, v11
	v_mfma_f32_32x32x16_f16 v[44:59], v[112:115], a[100:103], v[44:59]
	v_mul_f32_e32 v62, v72, v10
	v_mul_f32_e32 v63, v72, v11
	v_max_i32_e32 v12, 0, v12
	v_max_i32_e32 v13, 0, v13
	v_mul_f32_e32 v64, v72, v12
	v_mul_f32_e32 v65, v72, v13
	v_mfma_f32_32x32x16_f16 v[44:59], v[108:111], a[104:107], v[44:59]
	v_max_i32_e32 v14, 0, v14
	v_max_i32_e32 v15, 0, v15
	v_mul_f32_e32 v66, v72, v14
	v_mul_f32_e32 v67, v72, v15
	v_max_i32_e32 v16, 0, v16
	v_max_i32_e32 v17, 0, v17
	v_mfma_f32_32x32x16_f16 v[44:59], v[92:95], a[108:111], v[44:59]
	v_mul_f32_e32 v68, v72, v16
	v_mul_f32_e32 v69, v72, v17
	v_max_i32_e32 v18, 0, v18
	v_max_i32_e32 v19, 0, v19
	v_mul_f32_e32 v70, v72, v18
	v_mul_f32_e32 v71, v72, v19
	v_max_i32_e32 v20, 0, v20
	v_max_i32_e32 v21, 0, v21
	v_mul_f32_e32 v96, v72, v20
	v_mul_f32_e32 v97, v72, v21
	v_max_i32_e32 v22, 0, v22
	v_max_i32_e32 v23, 0, v23
	v_mul_f32_e32 v98, v72, v22
	v_mul_f32_e32 v99, v72, v23
	v_mfma_f32_32x32x16_f16 v[8:23], v[116:119], a[112:115], 0
	v_max_i32_e32 v24, 0, v24
	v_max_i32_e32 v25, 0, v25
	v_fmac_f32_e32 v60, v73, v24
	v_fmac_f32_e32 v61, v73, v25
	v_max_i32_e32 v26, 0, v26
	v_max_i32_e32 v27, 0, v27
	v_mfma_f32_32x32x16_f16 v[8:23], v[112:115], a[116:119], v[8:23]
	v_fmac_f32_e32 v62, v73, v26
	v_fmac_f32_e32 v63, v73, v27
	v_max_i32_e32 v28, 0, v28
	v_max_i32_e32 v29, 0, v29
	v_fmac_f32_e32 v64, v73, v28
	v_fmac_f32_e32 v65, v73, v29
	v_mfma_f32_32x32x16_f16 v[8:23], v[108:111], a[120:123], v[8:23]
	v_max_i32_e32 v30, 0, v30
	v_max_i32_e32 v31, 0, v31
	v_fmac_f32_e32 v66, v73, v30
	v_fmac_f32_e32 v67, v73, v31
	v_max_i32_e32 v32, 0, v32
	v_max_i32_e32 v33, 0, v33
	v_mfma_f32_32x32x16_f16 v[8:23], v[92:95], a[124:127], v[8:23]
	v_fmac_f32_e32 v68, v73, v32
	v_fmac_f32_e32 v69, v73, v33
	v_max_i32_e32 v34, 0, v34
	v_max_i32_e32 v35, 0, v35
	v_fmac_f32_e32 v70, v73, v34
	v_fmac_f32_e32 v71, v73, v35
	v_max_i32_e32 v36, 0, v36
	v_max_i32_e32 v37, 0, v37
	v_fmac_f32_e32 v96, v73, v36
	v_fmac_f32_e32 v97, v73, v37
	v_max_i32_e32 v38, 0, v38
	v_max_i32_e32 v39, 0, v39
	v_fmac_f32_e32 v98, v73, v38
	v_fmac_f32_e32 v99, v73, v39
	v_max_i32_e32 v44, 0, v44
	v_max_i32_e32 v45, 0, v45
	v_fmac_f32_e32 v60, v104, v44
	v_fmac_f32_e32 v61, v104, v45
	v_max_i32_e32 v46, 0, v46
	v_max_i32_e32 v47, 0, v47
	v_fmac_f32_e32 v62, v104, v46
	v_fmac_f32_e32 v63, v104, v47
	v_max_i32_e32 v48, 0, v48
	v_max_i32_e32 v49, 0, v49
	v_fmac_f32_e32 v64, v104, v48
	v_fmac_f32_e32 v65, v104, v49
	v_max_i32_e32 v50, 0, v50
	v_max_i32_e32 v51, 0, v51
	v_fmac_f32_e32 v66, v104, v50
	v_fmac_f32_e32 v67, v104, v51
	v_max_i32_e32 v52, 0, v52
	v_max_i32_e32 v53, 0, v53
	v_fmac_f32_e32 v68, v104, v52
	v_fmac_f32_e32 v69, v104, v53
	v_max_i32_e32 v54, 0, v54
	v_max_i32_e32 v55, 0, v55
	v_fmac_f32_e32 v70, v104, v54
	v_fmac_f32_e32 v71, v104, v55
	v_max_i32_e32 v56, 0, v56
	v_max_i32_e32 v57, 0, v57
	v_fmac_f32_e32 v96, v104, v56
	v_fmac_f32_e32 v97, v104, v57
	v_max_i32_e32 v58, 0, v58
	v_max_i32_e32 v59, 0, v59
	v_fmac_f32_e32 v98, v104, v58
	v_fmac_f32_e32 v99, v104, v59
	v_readfirstlane_b32 s8, v40
	v_lshlrev_b32_e32 v120, 5, v40
	v_or_b32_e32 v120, v120, v155
	v_max_i32_e32 v8, 0, v8
	v_max_i32_e32 v9, 0, v9
	v_fmac_f32_e32 v60, v75, v8
	v_fmac_f32_e32 v61, v75, v9
	v_max_i32_e32 v10, 0, v10
	v_max_i32_e32 v11, 0, v11
	v_fmac_f32_e32 v62, v75, v10
	v_fmac_f32_e32 v63, v75, v11
	v_max_i32_e32 v12, 0, v12
	v_max_i32_e32 v13, 0, v13
	v_fmac_f32_e32 v64, v75, v12
	v_fmac_f32_e32 v65, v75, v13
	v_max_i32_e32 v14, 0, v14
	v_max_i32_e32 v15, 0, v15
	v_fmac_f32_e32 v66, v75, v14
	v_fmac_f32_e32 v67, v75, v15
	v_max_i32_e32 v16, 0, v16
	v_max_i32_e32 v17, 0, v17
	v_fmac_f32_e32 v68, v75, v16
	v_fmac_f32_e32 v69, v75, v17
	v_max_i32_e32 v18, 0, v18
	v_max_i32_e32 v19, 0, v19
	v_fmac_f32_e32 v70, v75, v18
	v_fmac_f32_e32 v71, v75, v19
	v_max_i32_e32 v20, 0, v20
	v_max_i32_e32 v21, 0, v21
	v_fmac_f32_e32 v96, v75, v20
	v_fmac_f32_e32 v97, v75, v21
	v_max_i32_e32 v22, 0, v22
	v_max_i32_e32 v23, 0, v23
	v_fmac_f32_e32 v98, v75, v22
	v_fmac_f32_e32 v99, v75, v23
	s_cmp_lg_u32 s8, s75
	s_cbranch_scc1 .Lrd_nodiag
	v_mov_b32_e32 v130, 0xff800000
	v_or_b32_e32 v124, 0, v120
	v_cmp_gt_i32_e32 vcc, v124, v100
	s_nop 1
	v_cndmask_b32_e32 v60, v60, v130, vcc
	v_or_b32_e32 v124, 1, v120
	v_cmp_gt_i32_e32 vcc, v124, v100
	s_nop 1
	v_cndmask_b32_e32 v61, v61, v130, vcc
	v_or_b32_e32 v124, 2, v120
	v_cmp_gt_i32_e32 vcc, v124, v100
	s_nop 1
	v_cndmask_b32_e32 v62, v62, v130, vcc
	v_or_b32_e32 v124, 3, v120
	v_cmp_gt_i32_e32 vcc, v124, v100
	s_nop 1
	v_cndmask_b32_e32 v63, v63, v130, vcc
	v_or_b32_e32 v124, 8, v120
	v_cmp_gt_i32_e32 vcc, v124, v100
	s_nop 1
	v_cndmask_b32_e32 v64, v64, v130, vcc
	v_or_b32_e32 v124, 9, v120
	v_cmp_gt_i32_e32 vcc, v124, v100
	s_nop 1
	v_cndmask_b32_e32 v65, v65, v130, vcc
	v_or_b32_e32 v124, 10, v120
	v_cmp_gt_i32_e32 vcc, v124, v100
	s_nop 1
	v_cndmask_b32_e32 v66, v66, v130, vcc
	v_or_b32_e32 v124, 11, v120
	v_cmp_gt_i32_e32 vcc, v124, v100
	s_nop 1
	v_cndmask_b32_e32 v67, v67, v130, vcc
	v_or_b32_e32 v124, 16, v120
	v_cmp_gt_i32_e32 vcc, v124, v100
	s_nop 1
	v_cndmask_b32_e32 v68, v68, v130, vcc
	v_or_b32_e32 v124, 17, v120
	v_cmp_gt_i32_e32 vcc, v124, v100
	s_nop 1
	v_cndmask_b32_e32 v69, v69, v130, vcc
	v_or_b32_e32 v124, 18, v120
	v_cmp_gt_i32_e32 vcc, v124, v100
	s_nop 1
	v_cndmask_b32_e32 v70, v70, v130, vcc
	v_or_b32_e32 v124, 19, v120
	v_cmp_gt_i32_e32 vcc, v124, v100
	s_nop 1
	v_cndmask_b32_e32 v71, v71, v130, vcc
	v_or_b32_e32 v124, 24, v120
	v_cmp_gt_i32_e32 vcc, v124, v100
	s_nop 1
	v_cndmask_b32_e32 v96, v96, v130, vcc
	v_or_b32_e32 v124, 25, v120
	v_cmp_gt_i32_e32 vcc, v124, v100
	s_nop 1
	v_cndmask_b32_e32 v97, v97, v130, vcc
	v_or_b32_e32 v124, 26, v120
	v_cmp_gt_i32_e32 vcc, v124, v100
	s_nop 1
	v_cndmask_b32_e32 v98, v98, v130, vcc
	v_or_b32_e32 v124, 27, v120
	v_cmp_gt_i32_e32 vcc, v124, v100
	s_nop 1
	v_cndmask_b32_e32 v99, v99, v130, vcc
.Lrd_nodiag:
	s_waitcnt lgkmcnt(0)
	v_mov_b32_e32 v130, 0x18000
	v_mov_b32_e32 v122, 0
	v_cmp_lt_f32_e64 s[6:7], v151, v60
	v_cmp_lt_f32_e64 s[8:9], v151, v61
	v_cmp_lt_f32_e64 s[10:11], v151, v62
	v_cmp_lt_f32_e64 s[12:13], v151, v63
	v_cmp_lt_f32_e64 s[14:15], v151, v64
	v_cmp_lt_f32_e64 s[16:17], v151, v65
	v_cmp_lt_f32_e64 s[18:19], v151, v66
	v_cmp_lt_f32_e64 s[20:21], v151, v67
	v_addc_co_u32_e64 v122, vcc, 0, v122, s[6:7]
	v_addc_co_u32_e64 v122, vcc, 0, v122, s[8:9]
	v_addc_co_u32_e64 v122, vcc, 0, v122, s[10:11]
	v_addc_co_u32_e64 v122, vcc, 0, v122, s[12:13]
	v_addc_co_u32_e64 v122, vcc, 0, v122, s[14:15]
	v_addc_co_u32_e64 v122, vcc, 0, v122, s[16:17]
	v_addc_co_u32_e64 v122, vcc, 0, v122, s[18:19]
	v_addc_co_u32_e64 v122, vcc, 0, v122, s[20:21]
	v_cmp_lt_f32_e64 s[6:7], v151, v68
	v_cmp_lt_f32_e64 s[8:9], v151, v69
	v_cmp_lt_f32_e64 s[10:11], v151, v70
	v_cmp_lt_f32_e64 s[12:13], v151, v71
	v_cmp_lt_f32_e64 s[14:15], v151, v96
	v_cmp_lt_f32_e64 s[16:17], v151, v97
	v_cmp_lt_f32_e64 s[18:19], v151, v98
	v_cmp_lt_f32_e64 s[20:21], v151, v99
	v_addc_co_u32_e64 v122, vcc, 0, v122, s[6:7]
	v_addc_co_u32_e64 v122, vcc, 0, v122, s[8:9]
	v_addc_co_u32_e64 v122, vcc, 0, v122, s[10:11]
	v_addc_co_u32_e64 v122, vcc, 0, v122, s[12:13]
	v_addc_co_u32_e64 v122, vcc, 0, v122, s[14:15]
	v_addc_co_u32_e64 v122, vcc, 0, v122, s[16:17]
	v_addc_co_u32_e64 v122, vcc, 0, v122, s[18:19]
	v_addc_co_u32_e64 v122, vcc, 0, v122, s[20:21]
	s_nop 1
	v_cmp_ne_u32_e32 vcc, 0, v122
	s_cbranch_vccz .LBB0_138
	s_mov_b64 exec, vcc
	ds_add_rtn_u32 v123, v156, v122
	s_waitcnt lgkmcnt(0)
	v_add_u32_e32 v124, v123, v122
	v_cmp_lt_u32_e32 vcc, 0x280, v124
	s_cbranch_vccz .Lrd_nohit
	s_mov_b64 exec, vcc
	ds_write_b32 v131, v252
.Lrd_nohit:
	s_mov_b64 exec, s[2:3]
	v_add_u32_e32 v123, v123, v154
	s_mov_b64 exec, s[6:7]
	s_cbranch_execz .Lrd_app8
	v_add_f32_e32 v124, 0, v68
	v_lshlrev_b32_e32 v126, 2, v123
	v_lshl_add_u32 v128, v123, 1, v130
	v_or_b32_e32 v129, 16, v120
	ds_write_b32 v126, v124
	ds_write_b16 v128, v129
	v_add_u32_e32 v123, 1, v123

.Lrd_app7:
.LBB0_138:
	s_or_b64 exec, exec, s[2:3]
	s_waitcnt lgkmcnt(0)
	s_barrier
	ds_read_b32 v40, v131
	s_mov_b64 s[84:85], 0
	s_waitcnt lgkmcnt(0)
	v_readfirstlane_b32 s2, v40
	s_cmp_eq_u32 s2, 0
	s_cbranch_scc1 .LBB0_105
	s_mov_b64 s[2:3], 0
	s_and_saveexec_b64 s[6:7], s[4:5]
	s_cbranch_execz .LBB0_140
	ds_read_b32 v40, v157
	s_movk_i32 s2, 0x280
	s_waitcnt lgkmcnt(0)
	v_cmp_lt_i32_e32 vcc, s2, v40
	s_and_b64 s[2:3], vcc, exec
	s_cmp_eq_u64 s[2:3], 0
	s_cbranch_scc1 .LBB0_140
	s_movk_i32 s2, 576
	v_cmp_lt_i32_e32 vcc, s2, v40
	s_and_b64 s[2:3], vcc, exec

.LBB0_212:
	v_lshl_add_u32 v131, s78, 2, v43
	v_bfe_u32 v131, v131, 2, 1
	v_lshlrev_b32_e32 v131, 2, v131
	v_add_u32_e32 v131, 0x25478, v131
	ds_write_b32 v131, v41
	s_waitcnt lgkmcnt(0)
	s_barrier
	s_andn2_b64 vcc, exec, s[84:85]
	s_cbranch_vccnz .LBB0_105
	s_waitcnt lgkmcnt(0)
	ds_read_b32 v151, v158
	s_branch .LBB0_105
